# P5 S5 pass-1 wave items remapped so each batch's 224 items run on workgroups with bid%8 == b (lines shared by adjacent channel groups hit one L2)
# baseline (speedup 1.0000x reference)
.LBB0_955:
	s_or_b64 exec, exec, s[30:31]
	v_readlane_b32 s0, v251, 10
	s_mulk_i32 s0, 0x3200
	s_add_i32 s30, s0, 0
	s_add_u32 s54, s46, 0x17294000
	s_addc_u32 s55, s47, 0
	v_readlane_b32 s0, v251, 19
	v_readlane_b32 s36, v252, 0
	s_cmpk_gt_i32 s0, 0x6ff
	s_mov_b32 s1, 0
	v_readlane_b32 s46, v252, 10
	v_readlane_b32 s47, v252, 11
	s_waitcnt lgkmcnt(0)
	s_barrier
	v_readlane_b32 s37, v252, 1
	v_readlane_b32 s38, v252, 2
	v_readlane_b32 s39, v252, 3
	v_readlane_b32 s40, v252, 4
	v_readlane_b32 s41, v252, 5
	v_readlane_b32 s42, v252, 6
	v_readlane_b32 s43, v252, 7
	v_readlane_b32 s44, v252, 8
	v_readlane_b32 s45, v252, 9
	v_readlane_b32 s48, v252, 12
	v_readlane_b32 s49, v252, 13
	v_readlane_b32 s50, v252, 14
	v_readlane_b32 s51, v252, 15
	s_cbranch_scc1 .LBB0_980
	v_mov_b32_e32 v41, 0
	s_movk_i32 s4, 0x2600
	v_readlane_b32 s5, v251, 19
	s_lshr_b32 s0, s5, 3
	s_and_b32 s2, s0, 7
	s_mul_i32 s2, s2, 0xe0
	s_lshr_b32 s0, s0, 3
	s_lshl_b32 s0, s0, 3
	s_and_b32 s5, s5, 7
	s_add_i32 s5, s5, s0
	s_add_i32 s5, s5, s2
	s_branch .LBB0_958
